# scan output tile parked as DPP-exchanged 32-bit pairs; attention: static s_setprio 1 on waves 0-3 (on top of previous)
# baseline (speedup 1.0000x reference)
; __device__ __forceinline__ void scan_unit(const int unit, const Args& a, unsigned char* lds, const int mk_wid) {
;     ...
;               f32x16 o0 = f32x16{}, o1 = f32x16{};
; #pragma unroll
;               for (int ct = 0; ct < 4; ++ct)
; #pragma unroll
;                 for (int kb = 0; kb < 2; ++kb) { const int cb = ct * 32 + kb * 16;
;                     v4u sw; sw.x = pk2(S[ct][8 * kb + 0], S[ct][8 * kb + 1]); sw.y = pk2(S[ct][8 * kb + 2], S[ct][8 * kb + 3]); sw.z = pk2(S[ct][8 * kb + 4], S[ct][8 * kb + 5]); sw.w = pk2(S[ct][8 * kb + 6], S[ct][8 * kb + 7]);
;                     const bf16x8 sb = __builtin_bit_cast(bf16x8, sw);
;                     { const u16* p0 = qe + r32 * QP + cb + 4 * hi; const v2u lo = *(const v2u*)p0, hh = *(const v2u*)(p0 + 8); v4u aw = {lo.x, lo.y, hh.x, hh.y};
;                       o0 = __builtin_amdgcn_mfma_f32_32x32x16_bf16(__builtin_bit_cast(bf16x8, aw), sb, o0, 0, 0, 0); }
;                     { const u16* p1 = qe + (32 + r32) * QP + cb + 4 * hi; const v2u lo = *(const v2u*)p1, hh = *(const v2u*)(p1 + 8); v4u aw = {lo.x, lo.y, hh.x, hh.y};
;                       o1 = __builtin_amdgcn_mfma_f32_32x32x16_bf16(__builtin_bit_cast(bf16x8, aw), sb, o1, 0, 0, 0); } }
;               GLA_LOADV();
;               asm volatile("s_waitcnt lgkmcnt(0)" ::: "memory"); GLA_SBAR();
;               { const u16* a0 = am + r32 * AP + hi * 8; const u16* a1 = am + (32 + r32) * AP + hi * 8;
;                 o0 = __builtin_amdgcn_mfma_f32_32x32x16_bf16(*(const bf16x8*)(a0), GLA_PK(vl0, vh0), o0, 0, 0, 0);
;                 o0 = __builtin_amdgcn_mfma_f32_32x32x16_bf16(*(const bf16x8*)(a0 + 16), GLA_PK(vl1, vh1), o0, 0, 0, 0);
;                 o1 = __builtin_amdgcn_mfma_f32_32x32x16_bf16(*(const bf16x8*)(a1), GLA_PK(vl0, vh0), o1, 0, 0, 0);
;                 o1 = __builtin_amdgcn_mfma_f32_32x32x16_bf16(*(const bf16x8*)(a1 + 16), GLA_PK(vl1, vh1), o1, 0, 0, 0);
;                 o1 = __builtin_amdgcn_mfma_f32_32x32x16_bf16(*(const bf16x8*)(a1 + 32), GLA_PK(vl2, vh2), o1, 0, 0, 0);
;                 o1 = __builtin_amdgcn_mfma_f32_32x32x16_bf16(*(const bf16x8*)(a1 + 48), GLA_PK(vl3, vh3), o1, 0, 0, 0); }
;               { u16* ow = ot + (4 * hi) * 256 + vt * 32 + r32;
; #pragma unroll
;                 for (int r = 0; r < 16; ++r) { const int i0 = crow(r, 0); ow[i0 * 256] = f2bf(o0[r]); ow[(i0 + 32) * 256] = f2bf(o1[r]); } }
.LBB0_442:
	v_and_b32_e32 v168, 31, v64
	v_mul_u32_u24_e32 v64, 0x110, v168
	v_lshlrev_b32_e32 v65, 4, v157
	v_add3_u32 v144, 0, v64, v65
	ds_read_b128 v[170:173], v144
	ds_read_b128 v[174:177], v144 offset:32
	ds_read_b128 v[178:181], v144 offset:8704
	ds_read_b128 v[182:185], v144 offset:8736
	ds_read_b128 v[186:189], v144 offset:64
	ds_read_b128 v[190:193], v144 offset:8768
	ds_read_b128 v[194:197], v144 offset:96
	ds_read_b128 v[198:201], v144 offset:8800
	ds_read_b128 v[202:205], v144 offset:128
	ds_read_b128 v[206:209], v144 offset:8832
	ds_read_b128 v[210:213], v144 offset:160
	ds_read_b128 v[214:217], v144 offset:8864
	ds_read_b128 v[218:221], v144 offset:192
	ds_read_b128 v[222:225], v144 offset:8896
	ds_read_b128 v[226:229], v144 offset:224
	v_cvt_pk_bf16_f32 v80, v0, v1
	v_cvt_pk_bf16_f32 v81, v2, v3
	v_cvt_pk_bf16_f32 v82, v4, v5
	v_cvt_pk_bf16_f32 v83, v6, v7
	s_waitcnt lgkmcnt(14)
	s_nop 0
	v_mfma_f32_32x32x16_bf16 v[64:79], v[170:173], v[80:83], 0
	ds_read_b128 v[230:233], v144 offset:8928
	v_cvt_pk_bf16_f32 v140, v8, v9
	v_cvt_pk_bf16_f32 v141, v10, v11
	v_cvt_pk_bf16_f32 v142, v12, v13
	v_cvt_pk_bf16_f32 v143, v14, v15
	v_cvt_pk_bf16_f32 v160, v56, v57
	v_cvt_pk_bf16_f32 v161, v58, v59
	v_cvt_pk_bf16_f32 v162, v60, v61
	v_cvt_pk_bf16_f32 v163, v62, v63
	s_waitcnt lgkmcnt(14)
	s_nop 0
	v_mfma_f32_32x32x16_bf16 v[64:79], v[174:177], v[140:143], v[64:79]
	s_waitcnt lgkmcnt(13)
	v_mfma_f32_32x32x16_bf16 v[80:95], v[178:181], v[80:83], 0
	s_waitcnt lgkmcnt(12)
	v_mfma_f32_32x32x16_bf16 v[80:95], v[182:185], v[140:143], v[80:95]
	v_cvt_pk_bf16_f32 v140, v16, v17
	v_cvt_pk_bf16_f32 v141, v18, v19
	v_cvt_pk_bf16_f32 v142, v20, v21
	v_cvt_pk_bf16_f32 v143, v22, v23
	s_waitcnt lgkmcnt(11)
	s_nop 0
	v_mfma_f32_32x32x16_bf16 v[64:79], v[186:189], v[140:143], v[64:79]
	s_waitcnt lgkmcnt(10)
	v_mfma_f32_32x32x16_bf16 v[80:95], v[190:193], v[140:143], v[80:95]
	v_cvt_pk_bf16_f32 v140, v24, v25
	v_cvt_pk_bf16_f32 v141, v26, v27
	v_cvt_pk_bf16_f32 v142, v28, v29
	v_cvt_pk_bf16_f32 v143, v30, v31
	s_waitcnt lgkmcnt(9)
	s_nop 0
	v_mfma_f32_32x32x16_bf16 v[64:79], v[194:197], v[140:143], v[64:79]
	s_waitcnt lgkmcnt(8)
	v_mfma_f32_32x32x16_bf16 v[80:95], v[198:201], v[140:143], v[80:95]
	v_cvt_pk_bf16_f32 v140, v32, v33
	v_cvt_pk_bf16_f32 v141, v34, v35
	v_cvt_pk_bf16_f32 v142, v36, v37
	v_cvt_pk_bf16_f32 v143, v38, v39
	s_waitcnt lgkmcnt(7)
	s_nop 0
	v_mfma_f32_32x32x16_bf16 v[64:79], v[202:205], v[140:143], v[64:79]
	s_waitcnt lgkmcnt(6)
	v_mfma_f32_32x32x16_bf16 v[80:95], v[206:209], v[140:143], v[80:95]
	v_cvt_pk_bf16_f32 v140, v40, v41
	v_cvt_pk_bf16_f32 v141, v42, v43
	v_cvt_pk_bf16_f32 v142, v44, v45
	v_cvt_pk_bf16_f32 v143, v46, v47
	s_waitcnt lgkmcnt(5)
	s_nop 0
	v_mfma_f32_32x32x16_bf16 v[64:79], v[210:213], v[140:143], v[64:79]
	s_waitcnt lgkmcnt(4)
	v_mfma_f32_32x32x16_bf16 v[80:95], v[214:217], v[140:143], v[80:95]
	v_cvt_pk_bf16_f32 v140, v48, v49
	v_cvt_pk_bf16_f32 v141, v50, v51
	v_cvt_pk_bf16_f32 v142, v52, v53
	v_cvt_pk_bf16_f32 v143, v54, v55
	s_waitcnt lgkmcnt(3)
	s_nop 0
	v_mfma_f32_32x32x16_bf16 v[64:79], v[218:221], v[140:143], v[64:79]
	s_waitcnt lgkmcnt(2)
	v_mfma_f32_32x32x16_bf16 v[80:95], v[222:225], v[140:143], v[80:95]
	ds_read_b64_tr_b16 v[136:137], v158 offset:0
	s_waitcnt lgkmcnt(2)
	v_mfma_f32_32x32x16_bf16 v[64:79], v[226:229], v[160:163], v[64:79]
	ds_read_b64_tr_b16 v[138:139], v158 offset:0x800
	ds_read_b64_tr_b16 v[140:141], v158 offset:0x1000
	ds_read_b64_tr_b16 v[142:143], v158 offset:0x1800
	ds_read_b64_tr_b16 v[144:145], v158 offset:0x2000
	ds_read_b64_tr_b16 v[146:147], v158 offset:0x2800
	ds_read_b64_tr_b16 v[148:149], v158 offset:0x3000
	ds_read_b64_tr_b16 v[150:151], v158 offset:0x3800
	s_waitcnt lgkmcnt(0)
	v_mfma_f32_32x32x16_bf16 v[80:95], v[230:233], v[160:163], v[80:95]
	v_mul_u32_u24_e32 v158, 0x90, v168
	v_lshlrev_b32_e32 v159, 4, v157
	v_add3_u32 v166, s57, v158, v159
	ds_read_b128 v[158:161], v166
	ds_read_b128 v[162:165], v166 offset:32
	s_mov_b32 s34, s42
	s_waitcnt lgkmcnt(1)
	v_mfma_f32_32x32x16_bf16 v[64:79], v[158:161], v[136:139], v[64:79]
	s_waitcnt lgkmcnt(0)
	v_mfma_f32_32x32x16_bf16 v[64:79], v[162:165], v[140:143], v[64:79]
	ds_read_b128 v[158:161], v166 offset:4608
	ds_read_b128 v[162:165], v166 offset:4640
	s_waitcnt lgkmcnt(1)
	v_mfma_f32_32x32x16_bf16 v[80:95], v[158:161], v[136:139], v[80:95]
	s_waitcnt lgkmcnt(0)
; __device__ __forceinline__ int crow(int r, int hi) { return (r & 3) + 8 * (r >> 2) + 4 * hi; }
; __device__ __forceinline__ u16 f2bf(float f) { return (u16)(pk2(f, 0.f) & 0xffffu); }
; __device__ __forceinline__ void scan_unit(const int unit, const Args& a, unsigned char* lds, const int mk_wid) {
;     ...
;               { const u16* a0 = am + r32 * AP + hi * 8; const u16* a1 = am + (32 + r32) * AP + hi * 8;
;                 o0 = __builtin_amdgcn_mfma_f32_32x32x16_bf16(*(const bf16x8*)(a0), GLA_PK(vl0, vh0), o0, 0, 0, 0);
;                 o0 = __builtin_amdgcn_mfma_f32_32x32x16_bf16(*(const bf16x8*)(a0 + 16), GLA_PK(vl1, vh1), o0, 0, 0, 0);
;                 o1 = __builtin_amdgcn_mfma_f32_32x32x16_bf16(*(const bf16x8*)(a1), GLA_PK(vl0, vh0), o1, 0, 0, 0);
;                 o1 = __builtin_amdgcn_mfma_f32_32x32x16_bf16(*(const bf16x8*)(a1 + 16), GLA_PK(vl1, vh1), o1, 0, 0, 0);
;                 o1 = __builtin_amdgcn_mfma_f32_32x32x16_bf16(*(const bf16x8*)(a1 + 32), GLA_PK(vl2, vh2), o1, 0, 0, 0);
;                 o1 = __builtin_amdgcn_mfma_f32_32x32x16_bf16(*(const bf16x8*)(a1 + 48), GLA_PK(vl3, vh3), o1, 0, 0, 0); }
;               { u16* ow = ot + (4 * hi) * 256 + vt * 32 + r32;
; #pragma unroll
;                 for (int r = 0; r < 16; ++r) { const int i0 = crow(r, 0); ow[i0 * 256] = f2bf(o0[r]); ow[(i0 + 32) * 256] = f2bf(o1[r]); } }
	v_mfma_f32_32x32x16_bf16 v[80:95], v[162:165], v[140:143], v[80:95]
	ds_read_b128 v[158:161], v166 offset:4672
	ds_read_b128 v[162:165], v166 offset:4704
	v_lshlrev_b32_e32 v234, 11, v157
	v_lshlrev_b32_e32 v235, 1, v168
	v_add3_u32 v234, s49, v234, v235
	v_and_b32_e32 v235, 1, v168
	v_mul_u32_u24_e32 v235, 0x1fe, v235
	v_add_u32_e32 v234, v234, v235
	s_waitcnt lgkmcnt(1)
	v_mfma_f32_32x32x16_bf16 v[80:95], v[158:161], v[144:147], v[80:95]
	s_waitcnt lgkmcnt(0)
	v_mfma_f32_32x32x16_bf16 v[80:95], v[162:165], v[148:151], v[80:95]
	s_mov_b32 vcc_lo, 0x55555555
	s_mov_b32 vcc_hi, 0x55555555
	s_nop 1
	v_cndmask_b32_dpp v170, v65, v64, vcc quad_perm:[1,0,3,2] row_mask:0xf bank_mask:0xf
	v_cndmask_b32_dpp v171, v67, v66, vcc quad_perm:[1,0,3,2] row_mask:0xf bank_mask:0xf
	v_cndmask_b32_dpp v172, v69, v68, vcc quad_perm:[1,0,3,2] row_mask:0xf bank_mask:0xf
	v_cndmask_b32_dpp v173, v71, v70, vcc quad_perm:[1,0,3,2] row_mask:0xf bank_mask:0xf
	v_cndmask_b32_dpp v174, v73, v72, vcc quad_perm:[1,0,3,2] row_mask:0xf bank_mask:0xf
	v_cndmask_b32_dpp v175, v75, v74, vcc quad_perm:[1,0,3,2] row_mask:0xf bank_mask:0xf
	v_cndmask_b32_dpp v176, v77, v76, vcc quad_perm:[1,0,3,2] row_mask:0xf bank_mask:0xf
	v_cndmask_b32_dpp v177, v79, v78, vcc quad_perm:[1,0,3,2] row_mask:0xf bank_mask:0xf
	s_nop 1
	v_cndmask_b32_dpp v178, v81, v80, vcc quad_perm:[1,0,3,2] row_mask:0xf bank_mask:0xf
	v_cndmask_b32_dpp v179, v83, v82, vcc quad_perm:[1,0,3,2] row_mask:0xf bank_mask:0xf
	v_cndmask_b32_dpp v180, v85, v84, vcc quad_perm:[1,0,3,2] row_mask:0xf bank_mask:0xf
	v_cndmask_b32_dpp v181, v87, v86, vcc quad_perm:[1,0,3,2] row_mask:0xf bank_mask:0xf
	v_cndmask_b32_dpp v182, v89, v88, vcc quad_perm:[1,0,3,2] row_mask:0xf bank_mask:0xf
	v_cndmask_b32_dpp v183, v91, v90, vcc quad_perm:[1,0,3,2] row_mask:0xf bank_mask:0xf
	v_cndmask_b32_dpp v184, v93, v92, vcc quad_perm:[1,0,3,2] row_mask:0xf bank_mask:0xf
	v_cndmask_b32_dpp v185, v95, v94, vcc quad_perm:[1,0,3,2] row_mask:0xf bank_mask:0xf
	s_mov_b32 vcc_lo, 0xaaaaaaaa
	s_mov_b32 vcc_hi, 0xaaaaaaaa
	s_nop 1
	v_cndmask_b32_dpp v186, v64, v65, vcc quad_perm:[1,0,3,2] row_mask:0xf bank_mask:0xf
	v_cndmask_b32_dpp v187, v66, v67, vcc quad_perm:[1,0,3,2] row_mask:0xf bank_mask:0xf
	v_cndmask_b32_dpp v188, v68, v69, vcc quad_perm:[1,0,3,2] row_mask:0xf bank_mask:0xf
	v_cndmask_b32_dpp v189, v70, v71, vcc quad_perm:[1,0,3,2] row_mask:0xf bank_mask:0xf
	v_cndmask_b32_dpp v190, v72, v73, vcc quad_perm:[1,0,3,2] row_mask:0xf bank_mask:0xf
	v_cndmask_b32_dpp v191, v74, v75, vcc quad_perm:[1,0,3,2] row_mask:0xf bank_mask:0xf
	v_cndmask_b32_dpp v192, v76, v77, vcc quad_perm:[1,0,3,2] row_mask:0xf bank_mask:0xf
	v_cndmask_b32_dpp v193, v78, v79, vcc quad_perm:[1,0,3,2] row_mask:0xf bank_mask:0xf
	v_cndmask_b32_dpp v194, v80, v81, vcc quad_perm:[1,0,3,2] row_mask:0xf bank_mask:0xf
	v_cndmask_b32_dpp v195, v82, v83, vcc quad_perm:[1,0,3,2] row_mask:0xf bank_mask:0xf
	v_cndmask_b32_dpp v196, v84, v85, vcc quad_perm:[1,0,3,2] row_mask:0xf bank_mask:0xf
	v_cndmask_b32_dpp v197, v86, v87, vcc quad_perm:[1,0,3,2] row_mask:0xf bank_mask:0xf
	v_cndmask_b32_dpp v198, v88, v89, vcc quad_perm:[1,0,3,2] row_mask:0xf bank_mask:0xf
	v_cndmask_b32_dpp v199, v90, v91, vcc quad_perm:[1,0,3,2] row_mask:0xf bank_mask:0xf
	v_cndmask_b32_dpp v200, v92, v93, vcc quad_perm:[1,0,3,2] row_mask:0xf bank_mask:0xf
	v_cndmask_b32_dpp v201, v94, v95, vcc quad_perm:[1,0,3,2] row_mask:0xf bank_mask:0xf
	v_cvt_pk_bf16_f32 v170, v170, v186
	ds_write_b32 v234, v170
	v_cvt_pk_bf16_f32 v171, v171, v187
	ds_write_b32 v234, v171 offset:1024
	v_cvt_pk_bf16_f32 v172, v172, v188
	ds_write_b32 v234, v172 offset:4096
	v_cvt_pk_bf16_f32 v173, v173, v189
	ds_write_b32 v234, v173 offset:5120
	v_cvt_pk_bf16_f32 v174, v174, v190
	ds_write_b32 v234, v174 offset:8192
	v_cvt_pk_bf16_f32 v175, v175, v191
	ds_write_b32 v234, v175 offset:9216
	v_cvt_pk_bf16_f32 v176, v176, v192
	ds_write_b32 v234, v176 offset:12288
	v_cvt_pk_bf16_f32 v177, v177, v193
	ds_write_b32 v234, v177 offset:13312
	v_cvt_pk_bf16_f32 v178, v178, v194
	ds_write_b32 v234, v178 offset:16384
	v_cvt_pk_bf16_f32 v179, v179, v195
	ds_write_b32 v234, v179 offset:17408
	v_cvt_pk_bf16_f32 v180, v180, v196
	ds_write_b32 v234, v180 offset:20480
	v_cvt_pk_bf16_f32 v181, v181, v197
	ds_write_b32 v234, v181 offset:21504
	v_cvt_pk_bf16_f32 v182, v182, v198
	ds_write_b32 v234, v182 offset:24576
	v_cvt_pk_bf16_f32 v183, v183, v199
	ds_write_b32 v234, v183 offset:25600
	v_cvt_pk_bf16_f32 v184, v184, v200
	ds_write_b32 v234, v184 offset:28672
	v_cvt_pk_bf16_f32 v185, v185, v201
	ds_write_b32 v234, v185 offset:29696

; __device__ __forceinline__ int crow(int r, int hi) { return (r & 3) + 8 * (r >> 2) + 4 * hi; }
; __device__ __forceinline__ void attn_unit(const bf16* Qb, const bf16* __restrict__ Kh, const bf16* __restrict__ Vh, bf16* Ob, int seq, char* lds,
;                                           const float* __restrict__ rope, const float* __restrict__ qg, const int mk_wid) {
;     ...
;   if (hi == 0) li_l[r32] = l_reg; asm volatile("s_waitcnt lgkmcnt(0)" ::: "memory");
;   float rli[16];
; #pragma unroll
;   for (int r = 0; r < 16; ++r) rli[r] = __builtin_amdgcn_rcpf(li_l[crow(r, hi)]);
;   __syncthreads();
;   { int te = MK_TID; asm volatile("" : "+v"(te)); const int lane = te & 63, r32 = lane & 31, hi = lane >> 5;
;     unsigned short* stg = (unsigned short*)(lds + wid * 8192);
; #pragma unroll
;     for (int r = 0; r < 16; ++r) { const int orow = crow(r, hi);
; #pragma unroll
;       for (int d0 = 0; d0 < 4; ++d0) stg[orow * 128 + d0 * 32 + r32] = (unsigned short)(cvtpk(o[d0][r] * rli[r], 0.f) & 0xffffu); }
; __global__ void __launch_bounds__(512) mk_fwd(Args a) {
;     ...
;         __syncthreads();
;         const int xj = bx >> 3, xx = bx & 7;
;         const int nun = full ? (xj < 16 ? 3 : 5) : 0;
;         for (int i = 0; ; ++i) {
;             int bk, w;
;             if (full) { if (i >= nun) break; const int idx = (xj < 16) ? 80 + i * 16 + xj : i * 16 + (xj - 16); bk = (idx >> 5) * 8 + xx; w = idx & 31; }
;             else { const int u = i * G + bx; if (u >= 1024) break; bk = u >> 5; w = u & 31; }
;             const int b = bk >> 1, kvh = bk & 1, hq = kvh * 4 + (w >> 3), qb = w & 7;
;             const size_t qoff = ((size_t)b * T + (size_t)qb * 256) * 1024 + hq * 128;
;             const size_t koff = (size_t)b * TA * 256 + kvh * 128;
;             att::attn_unit(Qp + qoff, Kp + koff, Vp + koff, (att::bf16*)(ws + WS_Q) + qoff, TA, (char*)lds, rope + (size_t)qb * 256 * 128, a.in[8], mk_wid);
.LBB0_450:
	s_add_u32 s9, s38, 0x7200000
	s_addc_u32 s47, s39, 0
	s_add_u32 s60, s38, 0xb200000
	s_addc_u32 s61, s39, 0
	s_add_u32 s62, s38, 0xc400000
	s_addc_u32 s63, s39, 0
	s_add_u32 s64, s38, 0x200000
	s_addc_u32 s65, s39, 0
	s_lshl_b32 s2, s72, 2
	s_mov_b32 s12, 0
	s_add_i32 s67, s2, 0
	s_lshl_b32 s6, s70, 5
	s_lshl_b32 s2, s70, 13
	s_mov_b32 s7, s12
	s_ashr_i32 s69, s8, 3
	s_and_b32 s66, s8, 7
	s_add_i32 s67, s67, 0x10000
	s_add_i32 s68, s2, 0
	s_lshl_b64 s[34:35], s[6:7], 11
	s_cmp_lt_i32 s69, 16
	s_load_dwordx2 s[42:43], s[0:1], 0x40
	s_cselect_b32 s2, 0x50, -16
	s_cselect_b32 s7, 3, 5
	s_add_i32 s69, s69, s2
	s_add_u32 s44, s38, 0xc424000
	s_addc_u32 s45, s39, 0
	v_mov_b32_e32 v177, 0
	v_mov_b32_e32 v180, 0x358637bd
	s_mov_b32 s73, 0x800000
	s_mov_b32 s74, 0x42b504f3
	s_mov_b32 s46, 0x3e0293ee
	s_mov_b64 s[48:49], 0x8000
	s_mov_b64 s[50:51], 0xc000
	s_mov_b64 s[52:53], 0x10000
	s_mov_b64 s[54:55], 0x14000
	s_mov_b32 s75, 0xffff4000
	s_movk_i32 s76, 0x8000
	s_mov_b32 s77, 0xfedf4000
	s_mov_b32 s78, 0xfedf8000
	v_mov_b32_e32 v181, 0xf149f2ca
	v_mov_b32_e32 v182, 0x120000
	s_mov_b32 s79, 0
	s_waitcnt vmcnt(0) lgkmcnt(0)
	s_barrier
	s_cmp_lt_u32 s70, 4
	s_cbranch_scc0 .Lattn_prio_done
	s_setprio 1
.Lattn_prio_done:
	s_branch .LBB0_453
.LBB0_451:
	s_or_b64 exec, exec, s[4:5]
	s_waitcnt lgkmcnt(0)
	v_add_u32_e32 v72, s67, v176
	ds_read_b128 v[64:67], v72
	ds_read_b128 v[68:71], v72 offset:32
	s_add_u32 s2, s56, s34
	s_addc_u32 s3, s57, s35
	s_add_i32 s79, s79, 1
	s_waitcnt lgkmcnt(1)
	v_rcp_f32_e32 v73, v64
	v_rcp_f32_e32 v74, v65
	v_rcp_f32_e32 v75, v66
	v_rcp_f32_e32 v76, v67
	s_waitcnt lgkmcnt(0)
	v_rcp_f32_e32 v77, v68
	ds_read_b128 v[64:67], v72 offset:64
	v_rcp_f32_e32 v78, v69
	v_rcp_f32_e32 v79, v70
	v_rcp_f32_e32 v80, v71
	ds_read_b128 v[68:71], v72 offset:96
	s_waitcnt lgkmcnt(0)
	s_barrier
	v_mbcnt_lo_u32_b32 v72, -1, 0
	v_mbcnt_hi_u32_b32 v72, -1, v72
	v_mul_f32_e32 v0, v0, v73
	v_add_u32_e32 v72, s72, v72
	v_cvt_pk_bf16_f32 v0, v0, v177
	v_rcp_f32_e32 v64, v64
	v_and_b32_e32 v81, 31, v72
	v_lshlrev_b32_e32 v82, 5, v72
	v_lshlrev_b32_e32 v81, 1, v81
	v_and_b32_e32 v82, 0x400, v82
	v_add3_u32 v81, s68, v81, v82
	ds_write_b16 v81, v0
	v_mul_f32_e32 v0, v48, v73
	v_cvt_pk_bf16_f32 v0, v0, v177
	ds_write_b16 v81, v0 offset:64
	v_mul_f32_e32 v0, v32, v73
	v_cvt_pk_bf16_f32 v0, v0, v177
	ds_write_b16 v81, v0 offset:128
	v_mul_f32_e32 v0, v16, v73
	v_cvt_pk_bf16_f32 v0, v0, v177
	ds_write_b16 v81, v0 offset:192
	v_mul_f32_e32 v0, v1, v74
	v_cvt_pk_bf16_f32 v0, v0, v177
	ds_write_b16 v81, v0 offset:256
	v_mul_f32_e32 v0, v49, v74
	v_cvt_pk_bf16_f32 v0, v0, v177
	ds_write_b16 v81, v0 offset:320
	v_mul_f32_e32 v0, v33, v74
	v_cvt_pk_bf16_f32 v0, v0, v177
	ds_write_b16 v81, v0 offset:384
	v_mul_f32_e32 v0, v17, v74
	v_cvt_pk_bf16_f32 v0, v0, v177
	ds_write_b16 v81, v0 offset:448
	v_mul_f32_e32 v0, v2, v75
	v_cvt_pk_bf16_f32 v0, v0, v177
	ds_write_b16 v81, v0 offset:512
	v_mul_f32_e32 v0, v50, v75
	v_cvt_pk_bf16_f32 v0, v0, v177
	ds_write_b16 v81, v0 offset:576
	v_mul_f32_e32 v0, v34, v75
	v_cvt_pk_bf16_f32 v0, v0, v177
	ds_write_b16 v81, v0 offset:640
	v_mul_f32_e32 v0, v18, v75
	v_cvt_pk_bf16_f32 v0, v0, v177
	ds_write_b16 v81, v0 offset:704
	v_mul_f32_e32 v0, v3, v76
	v_cvt_pk_bf16_f32 v0, v0, v177
	ds_write_b16 v81, v0 offset:768
	v_mul_f32_e32 v0, v51, v76
	v_cvt_pk_bf16_f32 v0, v0, v177
	ds_write_b16 v81, v0 offset:832
	v_mul_f32_e32 v0, v35, v76
	v_cvt_pk_bf16_f32 v0, v0, v177
	ds_write_b16 v81, v0 offset:896
	v_mul_f32_e32 v0, v19, v76
	v_cvt_pk_bf16_f32 v0, v0, v177
	ds_write_b16 v81, v0 offset:960
	v_mul_f32_e32 v0, v4, v77
	v_cvt_pk_bf16_f32 v0, v0, v177
	ds_write_b16 v81, v0 offset:2048
	v_mul_f32_e32 v0, v52, v77
	v_cvt_pk_bf16_f32 v0, v0, v177
	ds_write_b16 v81, v0 offset:2112
	v_mul_f32_e32 v0, v36, v77
	v_cvt_pk_bf16_f32 v0, v0, v177
	ds_write_b16 v81, v0 offset:2176
	v_mul_f32_e32 v0, v20, v77
	v_cvt_pk_bf16_f32 v0, v0, v177
	ds_write_b16 v81, v0 offset:2240
	v_mul_f32_e32 v0, v5, v78
	v_cvt_pk_bf16_f32 v0, v0, v177
	ds_write_b16 v81, v0 offset:2304
	v_mul_f32_e32 v0, v53, v78
	v_cvt_pk_bf16_f32 v0, v0, v177
	ds_write_b16 v81, v0 offset:2368
	v_mul_f32_e32 v0, v37, v78
	v_cvt_pk_bf16_f32 v0, v0, v177
	ds_write_b16 v81, v0 offset:2432
	v_mul_f32_e32 v0, v21, v78
	v_cvt_pk_bf16_f32 v0, v0, v177
	ds_write_b16 v81, v0 offset:2496
	v_mul_f32_e32 v0, v6, v79
	v_cvt_pk_bf16_f32 v0, v0, v177
	ds_write_b16 v81, v0 offset:2560
	v_mul_f32_e32 v0, v54, v79
	v_cvt_pk_bf16_f32 v0, v0, v177
	ds_write_b16 v81, v0 offset:2624
	v_mul_f32_e32 v0, v38, v79
	v_cvt_pk_bf16_f32 v0, v0, v177
	ds_write_b16 v81, v0 offset:2688
	v_mul_f32_e32 v0, v22, v79
	v_cvt_pk_bf16_f32 v0, v0, v177
	ds_write_b16 v81, v0 offset:2752
	v_mul_f32_e32 v0, v7, v80
	v_cvt_pk_bf16_f32 v0, v0, v177
	ds_write_b16 v81, v0 offset:2816
	v_mul_f32_e32 v0, v55, v80
	v_cvt_pk_bf16_f32 v0, v0, v177
	ds_write_b16 v81, v0 offset:2880
	v_mul_f32_e32 v0, v39, v80
	v_cvt_pk_bf16_f32 v0, v0, v177
	ds_write_b16 v81, v0 offset:2944
	v_mul_f32_e32 v0, v23, v80
	v_cvt_pk_bf16_f32 v0, v0, v177
	ds_write_b16 v81, v0 offset:3008
	v_mul_f32_e32 v0, v8, v64
	v_cvt_pk_bf16_f32 v0, v0, v177
	ds_write_b16 v81, v0 offset:4096
; __device__ __forceinline__ int crow(int r, int hi) { return (r & 3) + 8 * (r >> 2) + 4 * hi; }
; __device__ __forceinline__ void attn_unit(const bf16* Qb, const bf16* __restrict__ Kh, const bf16* __restrict__ Vh, bf16* Ob, int seq, char* lds,
;                                           const float* __restrict__ rope, const float* __restrict__ qg, const int mk_wid) {
;     ...
;   for (int r = 0; r < 16; ++r) rli[r] = __builtin_amdgcn_rcpf(li_l[crow(r, hi)]);
;   __syncthreads();
;   { int te = MK_TID; asm volatile("" : "+v"(te)); const int lane = te & 63, r32 = lane & 31, hi = lane >> 5;
;     unsigned short* stg = (unsigned short*)(lds + wid * 8192);
; #pragma unroll
;     for (int r = 0; r < 16; ++r) { const int orow = crow(r, hi);
; #pragma unroll
;       for (int d0 = 0; d0 < 4; ++d0) stg[orow * 128 + d0 * 32 + r32] = (unsigned short)(cvtpk(o[d0][r] * rli[r], 0.f) & 0xffffu); }
;     asm volatile("s_waitcnt lgkmcnt(0)" ::: "memory");
;     bf16* Ow = Ob + (long)(wid * QBLK) * LDO;
; #pragma unroll
;     for (int i = 0; i < 8; ++i) { const int row = i * 4 + (lane >> 4), ch = lane & 15; const u32x4 v = *(const u32x4*)(stg + row * 128 + ch * 8); *(u32x4*)(Ow + (long)row * LDO + ch * 8) = v; } }
;   __syncthreads();
	v_mul_f32_e32 v0, v56, v64
	v_cvt_pk_bf16_f32 v0, v0, v177
	v_rcp_f32_e32 v65, v65
	ds_write_b16 v81, v0 offset:4160
	v_mul_f32_e32 v0, v40, v64
	v_cvt_pk_bf16_f32 v0, v0, v177
	ds_write_b16 v81, v0 offset:4224
	v_mul_f32_e32 v0, v24, v64
	v_cvt_pk_bf16_f32 v0, v0, v177
	ds_write_b16 v81, v0 offset:4288
	v_mul_f32_e32 v0, v9, v65
	v_cvt_pk_bf16_f32 v0, v0, v177
	ds_write_b16 v81, v0 offset:4352
	v_mul_f32_e32 v0, v57, v65
	v_cvt_pk_bf16_f32 v0, v0, v177
	v_rcp_f32_e32 v66, v66
	ds_write_b16 v81, v0 offset:4416
	v_mul_f32_e32 v0, v41, v65
	v_cvt_pk_bf16_f32 v0, v0, v177
	ds_write_b16 v81, v0 offset:4480
	v_mul_f32_e32 v0, v25, v65
	v_cvt_pk_bf16_f32 v0, v0, v177
	ds_write_b16 v81, v0 offset:4544
	v_mul_f32_e32 v0, v10, v66
	v_cvt_pk_bf16_f32 v0, v0, v177
	ds_write_b16 v81, v0 offset:4608
	v_mul_f32_e32 v0, v58, v66
	v_cvt_pk_bf16_f32 v0, v0, v177
	v_rcp_f32_e32 v67, v67
	ds_write_b16 v81, v0 offset:4672
	v_mul_f32_e32 v0, v42, v66
	v_cvt_pk_bf16_f32 v0, v0, v177
	ds_write_b16 v81, v0 offset:4736
	v_mul_f32_e32 v0, v26, v66
	v_cvt_pk_bf16_f32 v0, v0, v177
	ds_write_b16 v81, v0 offset:4800
	v_mul_f32_e32 v0, v11, v67
	v_cvt_pk_bf16_f32 v0, v0, v177
	ds_write_b16 v81, v0 offset:4864
	v_mul_f32_e32 v0, v59, v67
	v_cvt_pk_bf16_f32 v0, v0, v177
	v_rcp_f32_e32 v68, v68
	ds_write_b16 v81, v0 offset:4928
	v_mul_f32_e32 v0, v43, v67
	v_cvt_pk_bf16_f32 v0, v0, v177
	ds_write_b16 v81, v0 offset:4992
	v_mul_f32_e32 v0, v27, v67
	v_cvt_pk_bf16_f32 v0, v0, v177
	ds_write_b16 v81, v0 offset:5056
	v_mul_f32_e32 v0, v12, v68
	v_cvt_pk_bf16_f32 v0, v0, v177
	ds_write_b16 v81, v0 offset:6144
	v_mul_f32_e32 v0, v60, v68
	v_cvt_pk_bf16_f32 v0, v0, v177
	v_rcp_f32_e32 v69, v69
	ds_write_b16 v81, v0 offset:6208
	v_mul_f32_e32 v0, v44, v68
	v_cvt_pk_bf16_f32 v0, v0, v177
	ds_write_b16 v81, v0 offset:6272
	v_mul_f32_e32 v0, v28, v68
	v_cvt_pk_bf16_f32 v0, v0, v177
	ds_write_b16 v81, v0 offset:6336
	v_mul_f32_e32 v0, v13, v69
	v_cvt_pk_bf16_f32 v0, v0, v177
	ds_write_b16 v81, v0 offset:6400
	v_mul_f32_e32 v0, v61, v69
	v_cvt_pk_bf16_f32 v0, v0, v177
	v_rcp_f32_e32 v70, v70
	ds_write_b16 v81, v0 offset:6464
	v_mul_f32_e32 v0, v45, v69
	v_cvt_pk_bf16_f32 v0, v0, v177
	ds_write_b16 v81, v0 offset:6528
	v_mul_f32_e32 v0, v29, v69
	v_cvt_pk_bf16_f32 v0, v0, v177
	ds_write_b16 v81, v0 offset:6592
	v_mul_f32_e32 v0, v14, v70
	v_cvt_pk_bf16_f32 v0, v0, v177
	ds_write_b16 v81, v0 offset:6656
	v_mul_f32_e32 v0, v62, v70
	v_cvt_pk_bf16_f32 v0, v0, v177
	v_rcp_f32_e32 v71, v71
	ds_write_b16 v81, v0 offset:6720
	v_mul_f32_e32 v0, v46, v70
	v_cvt_pk_bf16_f32 v0, v0, v177
	ds_write_b16 v81, v0 offset:6784
	v_mul_f32_e32 v0, v30, v70
	v_cvt_pk_bf16_f32 v0, v0, v177
	ds_write_b16 v81, v0 offset:6848
	v_mul_f32_e32 v0, v15, v71
	v_cvt_pk_bf16_f32 v0, v0, v177
	ds_write_b16 v81, v0 offset:6912
	v_mul_f32_e32 v0, v63, v71
	v_cvt_pk_bf16_f32 v0, v0, v177
	ds_write_b16 v81, v0 offset:6976
	v_mul_f32_e32 v0, v47, v71
	v_cvt_pk_bf16_f32 v0, v0, v177
	ds_write_b16 v81, v0 offset:7040
	v_mul_f32_e32 v0, v31, v71
	v_cvt_pk_bf16_f32 v0, v0, v177
	ds_write_b16 v81, v0 offset:7104
	v_lshlrev_b32_e32 v0, 4, v72
	v_and_b32_e32 v176, 0xf0, v0
	v_bfe_u32 v12, v72, 4, 2
	v_add_u32_e32 v13, s68, v176
	s_waitcnt lgkmcnt(0)
	v_lshl_add_u32 v0, v12, 8, v13
	v_or_b32_e32 v14, 4, v12
	ds_read_b128 v[0:3], v0
	v_lshl_add_u32 v4, v14, 8, v13
	ds_read_b128 v[4:7], v4
	v_lshl_add_u64 v[8:9], s[2:3], 0, v[176:177]
	v_lshlrev_b32_e32 v176, 11, v12
	v_lshl_add_u64 v[10:11], v[8:9], 0, v[176:177]
	v_lshlrev_b32_e32 v176, 11, v14
	s_waitcnt lgkmcnt(1)
	global_store_dwordx4 v[10:11], v[0:3], off
	v_or_b32_e32 v14, 12, v12
	s_mov_b64 s[4:5], 0
	v_lshl_add_u64 v[0:1], v[8:9], 0, v[176:177]
	s_waitcnt lgkmcnt(0)
	global_store_dwordx4 v[0:1], v[4:7], off
	s_nop 1
	v_or_b32_e32 v4, 8, v12
	v_lshl_add_u32 v0, v4, 8, v13
	ds_read_b128 v[0:3], v0
	v_lshlrev_b32_e32 v176, 11, v4
	v_lshl_add_u32 v4, v14, 8, v13
	ds_read_b128 v[4:7], v4
	v_lshl_add_u64 v[10:11], v[8:9], 0, v[176:177]
	v_lshlrev_b32_e32 v176, 11, v14
	s_waitcnt lgkmcnt(1)
	global_store_dwordx4 v[10:11], v[0:3], off
	v_or_b32_e32 v14, 20, v12
	s_nop 0
	v_lshl_add_u64 v[0:1], v[8:9], 0, v[176:177]
	s_waitcnt lgkmcnt(0)
	global_store_dwordx4 v[0:1], v[4:7], off
	s_nop 1
	v_or_b32_e32 v4, 16, v12
	v_lshl_add_u32 v0, v4, 8, v13
	ds_read_b128 v[0:3], v0
	v_lshlrev_b32_e32 v176, 11, v4
	v_lshl_add_u32 v4, v14, 8, v13
	ds_read_b128 v[4:7], v4
	v_lshl_add_u64 v[10:11], v[8:9], 0, v[176:177]
	v_lshlrev_b32_e32 v176, 11, v14
	s_waitcnt lgkmcnt(1)
	global_store_dwordx4 v[10:11], v[0:3], off
	s_nop 1
	v_lshl_add_u64 v[0:1], v[8:9], 0, v[176:177]
	s_waitcnt lgkmcnt(0)
	global_store_dwordx4 v[0:1], v[4:7], off
	s_nop 1
	v_or_b32_e32 v4, 24, v12
	v_lshl_add_u32 v0, v4, 8, v13
	v_or_b32_e32 v12, 28, v12
	ds_read_b128 v[0:3], v0
	v_lshlrev_b32_e32 v176, 11, v4
	v_lshl_add_u32 v4, v12, 8, v13
	ds_read_b128 v[4:7], v4
	v_lshl_add_u64 v[10:11], v[8:9], 0, v[176:177]
	v_lshlrev_b32_e32 v176, 11, v12
	s_waitcnt lgkmcnt(1)
	global_store_dwordx4 v[10:11], v[0:3], off
	s_nop 1
	v_lshl_add_u64 v[0:1], v[8:9], 0, v[176:177]
	s_waitcnt lgkmcnt(0)
	global_store_dwordx4 v[0:1], v[4:7], off
	s_barrier

; __device__ __forceinline__ void p_weights(const Args& a, unsigned char* lds, const int mk_wid, const int item_lo, const int item_hi, const int blk_lo, const bool do_rope) {
;     const int tid = MK_TID, lane = tid & 63, wave = mk_wid;
;     float* scr = (float*)(lds + wave * 16384);
;     if ((int)blockIdx.x < blk_lo) return;
;     const int gw = ((int)blockIdx.x - blk_lo) * 8 + wave, NGW = ((int)gridDim.x - blk_lo) * 8;
;     unsigned char* ws = a.ws;
;     constexpr int I_IN = 16 * 216, I_SQ = 16 * 32, I_FI = 16 * 176, I_FO = 44 * 32;
;     constexpr int NITEMS = I_IN + 3 * I_SQ + I_FI + I_FO;
;     for (int it = item_lo + gw; it < (item_hi < NITEMS ? item_hi : NITEMS); it += NGW) {
;         int r = it;
;         if (r < I_IN) { const int kb = r / 216, nb = r % 216, n0 = 32 * nb; const bool zero = n0 >= 6688;
;             const int src = n0 < 4608 ? n0 : (n0 < 6656 ? n0 + 32 : n0 - 2048);
;             transpose_item(a.in[7], 6688, zero ? 0 : src, 64 * kb, (u16*)(ws + WS_WIN), 1024, n0, zero, scr, lane); continue; }
; __global__ void __launch_bounds__(512) mk_fwd(Args a) {
;     ...
;         if (full) p_weights(a, lds, mk_wid, WI_PROJ, WI_ALL, 128, false);
.LBB0_478:
	s_setprio 0
	s_andn2_b64 vcc, exec, s[28:29]
	s_cbranch_vccnz .LBB0_511
	s_andn2_b64 vcc, exec, s[10:11]
	v_mbcnt_lo_u32_b32 v0, -1, 0
	v_mbcnt_hi_u32_b32 v0, -1, v0
	s_cbranch_vccnz .LBB0_511
	s_lshl_b32 s2, s8, 3
	s_add_i32 s2, s2, s70
	s_add_i32 s9, s2, 0xf80
	s_cmpk_gt_i32 s9, 0x23ff
	s_cbranch_scc1 .LBB0_511
	v_and_b32_e32 v1, 7, v0
	s_lshl_b32 s2, s70, 14
	v_mov_b32_e32 v33, 0
	v_lshlrev_b32_e32 v32, 4, v1
	s_add_i32 s4, s2, 0
	v_lshl_add_u64 v[4:5], s[38:39], 0, v[32:33]
	s_mov_b64 s[2:3], 0x2400000
	v_lshl_add_u64 v[34:35], v[4:5], 0, s[2:3]
	s_mov_b64 s[2:3], 0x1800000
	v_lshl_add_u64 v[36:37], v[4:5], 0, s[2:3]
	s_load_dwordx4 s[12:15], s[0:1], 0x98
	s_load_dwordx2 s[2:3], s[0:1], 0x38
	v_bfe_u32 v50, v0, 3, 3
	v_add_u32_e32 v3, s4, v32
	v_mul_u32_u24_e32 v6, 0x84, v50
	v_lshlrev_b32_e32 v0, 2, v1
	v_lshlrev_b32_e32 v2, 3, v1
	v_mul_u32_u24_e32 v1, 0x420, v1
	v_lshlrev_b32_e32 v7, 2, v50
	s_mov_b64 s[6:7], 0x400000
	v_add_u32_e32 v55, v3, v6
	s_mov_b32 s5, 0
	v_or_b32_e32 v51, 8, v50
	v_or_b32_e32 v52, 16, v50
	v_or_b32_e32 v53, 24, v50
	v_add3_u32 v54, s4, v1, v7
	v_lshl_add_u64 v[38:39], v[4:5], 0, s[6:7]
	s_waitcnt lgkmcnt(0)
	v_lshl_add_u64 v[40:41], s[14:15], 0, v[32:33]
	v_lshl_add_u64 v[42:43], s[12:13], 0, v[32:33]
	v_lshl_add_u64 v[44:45], s[2:3], 0, v[32:33]
	s_lshl_b32 s12, s9, 5
	s_lshl_b32 s13, s9, 1
	v_add_u32_e32 v56, 0x420, v55
	v_add_u32_e32 v57, 0x428, v55
	v_add_u32_e32 v58, 0x840, v55
	v_add_u32_e32 v59, 0x848, v55
	v_add_u32_e32 v60, 0xc60, v55
	v_add_u32_e32 v61, 0xc68, v55
	v_add_u32_e32 v62, 0x1080, v55
	v_add_u32_e32 v63, 0x1088, v55
	v_add_u32_e32 v64, 0x14a0, v55
	v_add_u32_e32 v65, 0x14a8, v55
	v_add_u32_e32 v66, 0x18c0, v55
	v_add_u32_e32 v67, 0x18c8, v55
	v_add_u32_e32 v68, 0x1ce0, v55
	v_add_u32_e32 v69, 0x1ce8, v55
	s_mov_b32 s14, 0x2c000
	s_mov_b32 s15, 0x58000
	s_mov_b32 s16, 0x84000
	s_mov_b32 s17, 0xb0000
	s_mov_b32 s18, 0xdc000
	s_mov_b32 s19, 0x108000
	s_mov_b32 s20, 0x134000
	s_movk_i32 s21, 0x88
	s_mov_b32 s22, 0x1400000
	v_lshlrev_b32_e32 v32, 2, v0
	s_mov_b32 s23, 0x8000
	s_mov_b32 s24, 0x10000
	s_mov_b32 s25, 0x18000
	s_mov_b32 s26, 0x20000
	s_mov_b32 s27, 0x28000
	s_mov_b32 s28, 0x30000
	s_mov_b32 s29, 0x38000
	v_lshlrev_b32_e32 v46, 1, v2
	s_movk_i32 s30, 0x6880
	s_branch .LBB0_484
